# v87 + one static s_setprio 1 only for blocks < gridDim/2 in the GEMM main loops
# baseline (speedup 1.0000x reference)
.LBB1_54:
	v_readlane_b32 s4, v242, 0
	s_lshl_b32 s5, s2, 3
	s_and_b32 s6, s4, 7
	s_or_b32 s5, s6, s5
	s_mul_i32 s5, s5, s55
	s_ashr_i32 s4, s4, 3
	s_add_i32 s4, s5, s4
	s_cmpk_lt_i32 s4, 0x400
	s_mov_b64 s[40:41], -1
	s_cbranch_scc0 .LBB1_53
	s_ashr_i32 s5, s4, 31
	s_lshr_b32 s5, s5, 25
	s_add_i32 s5, s4, s5
	s_and_b32 s6, s5, 0xffffff80
	s_sub_i32 s7, s4, s6
	s_ashr_i32 s4, s7, 31
	s_lshr_b32 s4, s4, 29
	s_add_i32 s6, s7, s4
	s_and_b32 s4, s6, 0xfffff8
	s_sub_i32 s4, s7, s4
	s_lshl_b32 s5, s5, 4
	s_and_b32 s5, s5, 0xfffff800
	s_lshl_b32 s4, s4, 8
	s_add_i32 s4, s4, s5
	s_lshl_b32 s5, s6, 4
	v_mov_b32_e32 v134, v162
	s_and_b32 s40, s5, 0xffffff80
	s_movk_i32 s10, 0x78
	v_readfirstlane_b32 s5, v134
	v_lshrrev_b32_e32 v0, 3, v134
	v_and_b32_e32 v0, 6, v0
	s_and_b32 s8, s5, 0xffffffc0
	s_waitcnt lgkmcnt(0)
	v_bfe_u32 v2, v134, 2, 4
	v_lshrrev_b32_e64 v0, v0, s10
	s_add_i32 s8, s8, s4
	v_xor_b32_e32 v3, v0, v134
	v_or_b32_e32 v0, s8, v2
	v_ashrrev_i32_e32 v1, 31, v0
	v_lshlrev_b64 v[0:1], 11, v[0:1]
	v_lshlrev_b32_e32 v3, 4, v3
	v_lshl_add_u64 v[0:1], s[74:75], 0, v[0:1]
	v_and_b32_e32 v128, 48, v3
	s_load_dwordx16 s[80:95], s[0:1], 0xc0
	s_ashr_i32 s6, s5, 6
	v_lshl_add_u64 v[130:131], v[0:1], 0, v[128:129]
	v_or_b32_e32 v0, s40, v2
	v_lshl_add_u32 v0, s6, 5, v0
	v_ashrrev_i32_e32 v1, 31, v0
	v_lshlrev_b64 v[0:1], 11, v[0:1]
	s_waitcnt lgkmcnt(0)
	v_lshl_add_u64 v[0:1], s[92:93], 0, v[0:1]
	v_lshl_add_u64 v[132:133], v[0:1], 0, v[128:129]
	v_lshrrev_b32_e32 v0, 1, v134
	v_and_b32_e32 v0, 6, v0
	v_bfe_u32 v136, v134, 4, 2
	s_lshl_b32 s8, s6, 12
	v_lshrrev_b32_e64 v0, v0, s10
	v_and_b32_e32 v135, 15, v134
	s_lshl_b32 s9, s6, 11
	s_and_b32 s6, s5, 0xffffff80
	v_bitop3_b32 v0, v0, v136, 3 bitop3:0x6c
	s_and_b32 s5, s5, 64
	s_add_i32 s10, s8, 16
	v_lshlrev_b32_e32 v138, 4, v0
	v_or_b32_e32 v0, s5, v135
	s_mov_b32 m0, s10
	v_lshlrev_b32_e32 v139, 6, v0
	s_barrier
	v_lshl_add_u64 v[0:1], v[130:131], 0, s[34:35]
	s_add_i32 m0, s10, 0x400
	s_mov_b64 s[12:13], 0x10000
	v_lshl_add_u64 v[0:1], v[130:131], 0, s[12:13]
	s_add_i32 m0, s10, 0x800
	s_mov_b64 s[12:13], 0x18000
	v_lshl_add_u64 v[0:1], v[130:131], 0, s[12:13]
	s_add_i32 m0, s10, 0xc00
	s_sub_i32 s11, s10, s9
	s_add_i32 m0, s11, 0x4000
	v_lshl_add_u64 v[0:1], v[132:133], 0, s[34:35]
	s_add_i32 m0, s11, 0x4400
	s_mov_b64 s[12:13], 0x8040
	v_lshl_add_u64 v[0:1], v[130:131], 0, 64
	s_add_i32 m0, s10, 0x6000
	s_mov_b64 s[14:15], 0x10040
	v_lshl_add_u64 v[0:1], v[130:131], 0, s[12:13]
	s_add_i32 m0, s10, 0x6400
	v_or_b32_e32 v128, s6, v135
	v_lshl_add_u64 v[0:1], v[130:131], 0, s[14:15]
	s_add_i32 m0, s10, 0x6800
	s_mov_b64 s[14:15], 0x18040
	v_lshl_add_u64 v[0:1], v[130:131], 0, s[14:15]
	s_add_i32 m0, s10, 0x6c00
	v_lshlrev_b32_e32 v137, 6, v128
	v_lshl_add_u64 v[0:1], v[132:133], 0, 64
	s_add_i32 m0, s11, 0xa000
	s_mov_b32 s10, 0
	v_lshl_add_u64 v[0:1], v[132:133], 0, s[12:13]
	s_add_i32 m0, s11, 0xa400
	s_mov_b32 s11, 0
	v_mov_b32_e32 v0, 0
	v_mov_b32_e32 v1, v0
	v_mov_b32_e32 v2, v0
	v_mov_b32_e32 v3, v0
	v_mov_b32_e32 v4, v0
	v_mov_b32_e32 v5, v0
	v_mov_b32_e32 v6, v0
	v_mov_b32_e32 v7, v0
	v_mov_b32_e32 v8, v0
	v_mov_b32_e32 v9, v0
	v_mov_b32_e32 v10, v0
	v_mov_b32_e32 v11, v0
	v_mov_b32_e32 v12, v0
	v_mov_b32_e32 v13, v0
	v_mov_b32_e32 v14, v0
	v_mov_b32_e32 v15, v0
	v_mov_b32_e32 v16, v0
	v_mov_b32_e32 v17, v0
	v_mov_b32_e32 v18, v0
	v_mov_b32_e32 v19, v0
	v_mov_b32_e32 v20, v0
	v_mov_b32_e32 v21, v0
	v_mov_b32_e32 v22, v0
	v_mov_b32_e32 v23, v0
	v_mov_b32_e32 v24, v0
	v_mov_b32_e32 v25, v0
	v_mov_b32_e32 v26, v0
	v_mov_b32_e32 v27, v0
	v_mov_b32_e32 v28, v0
	v_mov_b32_e32 v29, v0
	v_mov_b32_e32 v30, v0
	v_mov_b32_e32 v31, v0
	v_mov_b32_e32 v32, v0
	v_mov_b32_e32 v33, v0
	v_mov_b32_e32 v34, v0
	v_mov_b32_e32 v35, v0
	v_mov_b32_e32 v36, v0
	v_mov_b32_e32 v37, v0
	v_mov_b32_e32 v38, v0
	v_mov_b32_e32 v39, v0
	v_mov_b32_e32 v40, v0
	v_mov_b32_e32 v41, v0
	v_mov_b32_e32 v42, v0
	v_mov_b32_e32 v43, v0
	v_mov_b32_e32 v44, v0
	v_mov_b32_e32 v45, v0
	v_mov_b32_e32 v46, v0
	v_mov_b32_e32 v47, v0
	v_mov_b32_e32 v48, v0
	v_mov_b32_e32 v49, v0
	v_mov_b32_e32 v50, v0
	v_mov_b32_e32 v51, v0
	v_mov_b32_e32 v52, v0
	v_mov_b32_e32 v53, v0
	v_mov_b32_e32 v54, v0
	v_mov_b32_e32 v55, v0
	v_mov_b32_e32 v56, v0
	v_mov_b32_e32 v57, v0
	v_mov_b32_e32 v58, v0
	v_mov_b32_e32 v59, v0
	v_mov_b32_e32 v60, v0
	v_mov_b32_e32 v61, v0
	v_mov_b32_e32 v62, v0
	v_mov_b32_e32 v63, v0
	v_mov_b32_e32 v64, v0
	v_mov_b32_e32 v65, v0
	v_mov_b32_e32 v66, v0
	v_mov_b32_e32 v67, v0
	v_mov_b32_e32 v68, v0
	v_mov_b32_e32 v69, v0
	v_mov_b32_e32 v70, v0
	v_mov_b32_e32 v71, v0
	v_mov_b32_e32 v72, v0
	v_mov_b32_e32 v73, v0
	v_mov_b32_e32 v74, v0
	v_mov_b32_e32 v75, v0
	v_mov_b32_e32 v84, v0
	v_mov_b32_e32 v85, v0
	v_mov_b32_e32 v86, v0
	v_mov_b32_e32 v87, v0
	v_mov_b32_e32 v96, v0
	v_mov_b32_e32 v97, v0
	v_mov_b32_e32 v98, v0
	v_mov_b32_e32 v99, v0
	v_mov_b32_e32 v100, v0
	v_mov_b32_e32 v101, v0
	v_mov_b32_e32 v102, v0
	v_mov_b32_e32 v103, v0
	v_mov_b32_e32 v104, v0
	v_mov_b32_e32 v105, v0
	v_mov_b32_e32 v106, v0
	v_mov_b32_e32 v107, v0
	v_mov_b32_e32 v108, v0
	v_mov_b32_e32 v109, v0
	v_mov_b32_e32 v110, v0
	v_mov_b32_e32 v111, v0
	v_mov_b32_e32 v112, v0
	v_mov_b32_e32 v113, v0
	v_mov_b32_e32 v114, v0
	v_mov_b32_e32 v115, v0
	v_mov_b32_e32 v116, v0
	v_mov_b32_e32 v117, v0
	v_mov_b32_e32 v118, v0
	v_mov_b32_e32 v119, v0
	v_mov_b32_e32 v120, v0
	v_mov_b32_e32 v121, v0
	v_mov_b32_e32 v122, v0
	v_mov_b32_e32 v123, v0
	v_mov_b32_e32 v124, v0
	v_mov_b32_e32 v125, v0
	v_mov_b32_e32 v126, v0
	v_mov_b32_e32 v127, v0
	v_mov_b32_e32 v76, v0
	v_mov_b32_e32 v77, v0
	v_mov_b32_e32 v78, v0
	v_mov_b32_e32 v79, v0
	v_mov_b32_e32 v80, v0
	v_mov_b32_e32 v81, v0
	v_mov_b32_e32 v82, v0
	v_mov_b32_e32 v83, v0
	v_mov_b32_e32 v88, v0
	v_mov_b32_e32 v89, v0
	v_mov_b32_e32 v90, v0
	v_mov_b32_e32 v91, v0
	v_mov_b32_e32 v92, v0
	v_mov_b32_e32 v93, v0
	v_mov_b32_e32 v94, v0
	v_mov_b32_e32 v95, v0
	s_mov_b64 s[16:17], 0x10080
	v_and_b32_e32 v204, 15, v168
	v_lshrrev_b32_e32 v205, 4, v168
	v_bfe_u32 v206, v168, 1, 3
	v_xor_b32_e32 v205, v205, v206
	v_lshlrev_b32_e32 v205, 4, v205
	v_readfirstlane_b32 s15, v162
	v_readfirstlane_b32 s18, v130
	v_readfirstlane_b32 s19, v131
	v_readfirstlane_b32 s28, v132
	v_readfirstlane_b32 s29, v133
	s_lshr_b32 s15, s15, 6
	s_lshl_b32 s54, s15, 12
	s_lshr_b32 s41, s15, 1
	s_and_b32 s42, s15, 1
	v_lshl_add_u32 v206, s41, 6, v204
	v_lshl_add_u32 v196, v206, 7, v205
	v_xor_b32_e32 v197, 64, v196
	v_lshl_add_u32 v206, s42, 6, v204
	v_lshl_add_u32 v198, v206, 7, v205
	v_xor_b32_e32 v199, 64, v198
	v_add_u32_e32 v198, 0xc010, v198
	v_add_u32_e32 v199, 0xc010, v199
	v_lshrrev_b32_e32 v206, 3, v168
	v_and_b32_e32 v207, 7, v168
	v_lshrrev_b32_e32 v204, 1, v206
	v_xor_b32_e32 v207, v207, v204
	v_lshlrev_b32_e32 v207, 4, v207
	v_lshl_add_u32 v200, v206, 11, v207
	v_xor_b32_e32 v201, 64, v200
	s_lshl_b32 s42, s42, 16
	s_sub_u32 s18, s18, s42
	s_subb_u32 s19, s19, 0
	s_add_i32 s41, s54, 16
	s_add_i32 m0, s41, 0x0
	s_nop 0
	global_load_lds_dwordx4 v200, s[18:19]
	s_add_i32 m0, s41, 0x400
	s_add_u32 s52, s18, 0x4000
	s_addc_u32 s53, s19, 0
	global_load_lds_dwordx4 v201, s[52:53]
	s_add_i32 m0, s41, 0x800
	s_add_u32 s52, s18, 0x8000
	s_addc_u32 s53, s19, 0
	global_load_lds_dwordx4 v200, s[52:53]
	s_add_i32 m0, s41, 0xc00
	s_add_u32 s52, s18, 0xc000
	s_addc_u32 s53, s19, 0
	global_load_lds_dwordx4 v201, s[52:53]
	s_add_i32 m0, s54, 0xc010
	s_nop 0
	global_load_lds_dwordx4 v200, s[28:29]
	s_add_i32 m0, s54, 0xc410
	s_add_u32 s52, s28, 0x4000
	s_addc_u32 s53, s29, 0
	global_load_lds_dwordx4 v201, s[52:53]
	s_add_i32 m0, s54, 0xc810
	s_add_u32 s52, s28, 0x8000
	s_addc_u32 s53, s29, 0
	global_load_lds_dwordx4 v200, s[52:53]
	s_add_i32 m0, s54, 0xcc10
	s_add_u32 s52, s28, 0xc000
	s_addc_u32 s53, s29, 0
	global_load_lds_dwordx4 v201, s[52:53]
	s_add_u32 s50, s18, 0x20000
	s_addc_u32 s51, s19, 0
	s_add_i32 m0, s41, 0x4000
	s_nop 0
	global_load_lds_dwordx4 v200, s[50:51]
	s_add_i32 m0, s41, 0x4400
	s_add_u32 s52, s50, 0x4000
	s_addc_u32 s53, s51, 0
	global_load_lds_dwordx4 v201, s[52:53]
	s_add_i32 m0, s41, 0x4800
	s_add_u32 s52, s50, 0x8000
	s_addc_u32 s53, s51, 0
	global_load_lds_dwordx4 v200, s[52:53]
	s_add_i32 m0, s41, 0x4c00
	s_add_u32 s52, s50, 0xc000
	s_addc_u32 s53, s51, 0
	global_load_lds_dwordx4 v201, s[52:53]
	s_mov_b32 s13, 0
	s_mov_b32 s14, 0
	v_readlane_b32 s15, v242, 0
	v_readlane_b32 s41, v241, 24
	s_nop 3
	s_lshr_b32 s41, s41, 3
	s_cmp_lt_u32 s15, s41
	s_cbranch_scc0 .Lprio_done_LBB1_56
	s_setprio 1

.Lg96pf_skip_LBB1_82:
	s_mov_b32 s59, 0
	s_mov_b32 s18, 0
	s_waitcnt vmcnt(0)
	s_barrier
	v_readlane_b32 s19, v242, 0
	v_readlane_b32 s13, v241, 24
	s_nop 3
	s_lshr_b32 s13, s13, 3
	s_cmp_lt_u32 s19, s13
	s_cbranch_scc0 .Lprio_done_LBB1_82
	s_setprio 1

.LBB1_1179:
	v_mov_b32_e32 v138, v162
	s_lshl_b32 s6, s5, 8
	v_readfirstlane_b32 s7, v138
	v_lshrrev_b32_e32 v0, 3, v138
	v_and_b32_e32 v0, 6, v0
	s_movk_i32 s11, 0x78
	s_and_b32 s9, s7, 0xffffffc0
	s_waitcnt lgkmcnt(0)
	v_bfe_u32 v2, v138, 2, 4
	v_lshrrev_b32_e64 v0, v0, s11
	s_add_i32 s9, s9, s6
	v_xor_b32_e32 v3, v0, v138
	v_or_b32_e32 v0, s9, v2
	v_ashrrev_i32_e32 v1, 31, v0
	v_lshlrev_b64 v[0:1], 11, v[0:1]
	v_lshlrev_b32_e32 v3, 4, v3
	s_lshl_b32 s30, s4, 7
	v_lshl_add_u64 v[0:1], s[74:75], 0, v[0:1]
	v_and_b32_e32 v128, 48, v3
	s_load_dwordx16 s[80:95], s[0:1], 0xc0
	s_ashr_i32 s8, s7, 6
	v_lshl_add_u64 v[130:131], v[0:1], 0, v[128:129]
	v_or_b32_e32 v0, s30, v2
	v_lshl_add_u32 v0, s8, 5, v0
	v_ashrrev_i32_e32 v1, 31, v0
	v_lshlrev_b64 v[0:1], 11, v[0:1]
	s_waitcnt lgkmcnt(0)
	v_lshl_add_u64 v[0:1], s[84:85], 0, v[0:1]
	v_lshl_add_u64 v[132:133], v[0:1], 0, v[128:129]
	v_lshrrev_b32_e32 v0, 1, v138
	v_and_b32_e32 v0, 6, v0
	v_bfe_u32 v140, v138, 4, 2
	s_lshl_b32 s9, s8, 12
	v_lshrrev_b32_e64 v0, v0, s11
	v_and_b32_e32 v139, 15, v138
	s_lshl_b32 s10, s8, 11
	s_and_b32 s8, s7, 0xffffff80
	v_bitop3_b32 v0, v0, v140, 3 bitop3:0x6c
	s_and_b32 s7, s7, 64
	s_add_i32 s11, s9, 16
	v_lshlrev_b32_e32 v134, 4, v0
	v_or_b32_e32 v0, s7, v139
	s_mov_b32 m0, s11
	v_lshlrev_b32_e32 v135, 6, v0
	s_barrier
	v_lshl_add_u64 v[0:1], v[130:131], 0, s[34:35]
	s_add_i32 m0, s11, 0x400
	s_mov_b64 s[12:13], 0x10000
	v_lshl_add_u64 v[0:1], v[130:131], 0, s[12:13]
	s_add_i32 m0, s11, 0x800
	s_mov_b64 s[12:13], 0x18000
	v_lshl_add_u64 v[0:1], v[130:131], 0, s[12:13]
	s_add_i32 m0, s11, 0xc00
	s_sub_i32 s12, s11, s10
	s_add_i32 m0, s12, 0x4000
	v_lshl_add_u64 v[0:1], v[132:133], 0, s[34:35]
	s_add_i32 m0, s12, 0x4400
	s_mov_b64 s[14:15], 0x8040
	v_lshl_add_u64 v[0:1], v[130:131], 0, 64
	s_add_i32 m0, s11, 0x6000
	s_mov_b64 s[16:17], 0x10040
	v_lshl_add_u64 v[0:1], v[130:131], 0, s[14:15]
	s_add_i32 m0, s11, 0x6400
	v_or_b32_e32 v141, s8, v139
	v_lshl_add_u64 v[0:1], v[130:131], 0, s[16:17]
	s_add_i32 m0, s11, 0x6800
	s_mov_b64 s[16:17], 0x18040
	v_lshl_add_u64 v[0:1], v[130:131], 0, s[16:17]
	s_add_i32 m0, s11, 0x6c00
	v_lshlrev_b32_e32 v128, 6, v141
	v_lshl_add_u64 v[0:1], v[132:133], 0, 64
	s_add_i32 m0, s12, 0xa000
	s_mov_b32 s11, 0
	v_lshl_add_u64 v[0:1], v[132:133], 0, s[14:15]
	s_add_i32 m0, s12, 0xa400
	s_mov_b32 s12, 0
	v_mov_b32_e32 v0, 0
	v_mov_b32_e32 v1, v0
	v_mov_b32_e32 v2, v0
	v_mov_b32_e32 v3, v0
	v_mov_b32_e32 v4, v0
	v_mov_b32_e32 v5, v0
	v_mov_b32_e32 v6, v0
	v_mov_b32_e32 v7, v0
	v_mov_b32_e32 v8, v0
	v_mov_b32_e32 v9, v0
	v_mov_b32_e32 v10, v0
	v_mov_b32_e32 v11, v0
	v_mov_b32_e32 v12, v0
	v_mov_b32_e32 v13, v0
	v_mov_b32_e32 v14, v0
	v_mov_b32_e32 v15, v0
	v_mov_b32_e32 v16, v0
	v_mov_b32_e32 v17, v0
	v_mov_b32_e32 v18, v0
	v_mov_b32_e32 v19, v0
	v_mov_b32_e32 v20, v0
	v_mov_b32_e32 v21, v0
	v_mov_b32_e32 v22, v0
	v_mov_b32_e32 v23, v0
	v_mov_b32_e32 v24, v0
	v_mov_b32_e32 v25, v0
	v_mov_b32_e32 v26, v0
	v_mov_b32_e32 v27, v0
	v_mov_b32_e32 v28, v0
	v_mov_b32_e32 v29, v0
	v_mov_b32_e32 v30, v0
	v_mov_b32_e32 v31, v0
	v_mov_b32_e32 v32, v0
	v_mov_b32_e32 v33, v0
	v_mov_b32_e32 v34, v0
	v_mov_b32_e32 v35, v0
	v_mov_b32_e32 v36, v0
	v_mov_b32_e32 v37, v0
	v_mov_b32_e32 v38, v0
	v_mov_b32_e32 v39, v0
	v_mov_b32_e32 v40, v0
	v_mov_b32_e32 v41, v0
	v_mov_b32_e32 v42, v0
	v_mov_b32_e32 v43, v0
	v_mov_b32_e32 v44, v0
	v_mov_b32_e32 v45, v0
	v_mov_b32_e32 v46, v0
	v_mov_b32_e32 v47, v0
	v_mov_b32_e32 v48, v0
	v_mov_b32_e32 v49, v0
	v_mov_b32_e32 v50, v0
	v_mov_b32_e32 v51, v0
	v_mov_b32_e32 v68, v0
	v_mov_b32_e32 v69, v0
	v_mov_b32_e32 v70, v0
	v_mov_b32_e32 v71, v0
	v_mov_b32_e32 v72, v0
	v_mov_b32_e32 v73, v0
	v_mov_b32_e32 v74, v0
	v_mov_b32_e32 v75, v0
	v_mov_b32_e32 v76, v0
	v_mov_b32_e32 v77, v0
	v_mov_b32_e32 v78, v0
	v_mov_b32_e32 v79, v0
	v_mov_b32_e32 v80, v0
	v_mov_b32_e32 v81, v0
	v_mov_b32_e32 v82, v0
	v_mov_b32_e32 v83, v0
	v_mov_b32_e32 v84, v0
	v_mov_b32_e32 v85, v0
	v_mov_b32_e32 v86, v0
	v_mov_b32_e32 v87, v0
	v_mov_b32_e32 v88, v0
	v_mov_b32_e32 v89, v0
	v_mov_b32_e32 v90, v0
	v_mov_b32_e32 v91, v0
	v_mov_b32_e32 v92, v0
	v_mov_b32_e32 v93, v0
	v_mov_b32_e32 v94, v0
	v_mov_b32_e32 v95, v0
	v_mov_b32_e32 v96, v0
	v_mov_b32_e32 v97, v0
	v_mov_b32_e32 v98, v0
	v_mov_b32_e32 v99, v0
	v_mov_b32_e32 v100, v0
	v_mov_b32_e32 v101, v0
	v_mov_b32_e32 v102, v0
	v_mov_b32_e32 v103, v0
	v_mov_b32_e32 v104, v0
	v_mov_b32_e32 v105, v0
	v_mov_b32_e32 v106, v0
	v_mov_b32_e32 v107, v0
	v_mov_b32_e32 v108, v0
	v_mov_b32_e32 v109, v0
	v_mov_b32_e32 v110, v0
	v_mov_b32_e32 v111, v0
	v_mov_b32_e32 v112, v0
	v_mov_b32_e32 v113, v0
	v_mov_b32_e32 v114, v0
	v_mov_b32_e32 v115, v0
	v_mov_b32_e32 v116, v0
	v_mov_b32_e32 v117, v0
	v_mov_b32_e32 v118, v0
	v_mov_b32_e32 v119, v0
	v_mov_b32_e32 v120, v0
	v_mov_b32_e32 v121, v0
	v_mov_b32_e32 v122, v0
	v_mov_b32_e32 v123, v0
	v_mov_b32_e32 v124, v0
	v_mov_b32_e32 v125, v0
	v_mov_b32_e32 v126, v0
	v_mov_b32_e32 v127, v0
	v_mov_b32_e32 v60, v0
	v_mov_b32_e32 v61, v0
	v_mov_b32_e32 v62, v0
	v_mov_b32_e32 v63, v0
	v_mov_b32_e32 v64, v0
	v_mov_b32_e32 v65, v0
	v_mov_b32_e32 v66, v0
	v_mov_b32_e32 v67, v0
	v_mov_b32_e32 v52, v0
	v_mov_b32_e32 v53, v0
	v_mov_b32_e32 v54, v0
	v_mov_b32_e32 v55, v0
	v_mov_b32_e32 v56, v0
	v_mov_b32_e32 v57, v0
	v_mov_b32_e32 v58, v0
	v_mov_b32_e32 v59, v0
	s_mov_b64 s[16:17], 0x10080
	v_and_b32_e32 v204, 15, v168
	v_lshrrev_b32_e32 v205, 4, v168
	v_bfe_u32 v206, v168, 1, 3
	v_xor_b32_e32 v205, v205, v206
	v_lshlrev_b32_e32 v205, 4, v205
	v_readfirstlane_b32 s15, v162
	v_readfirstlane_b32 s18, v130
	v_readfirstlane_b32 s19, v131
	v_readfirstlane_b32 s28, v132
	v_readfirstlane_b32 s29, v133
	s_lshr_b32 s15, s15, 6
	s_lshl_b32 s54, s15, 12
	s_lshr_b32 s41, s15, 1
	s_and_b32 s42, s15, 1
	v_lshl_add_u32 v206, s41, 6, v204
	v_lshl_add_u32 v196, v206, 7, v205
	v_xor_b32_e32 v197, 64, v196
	v_lshl_add_u32 v206, s42, 6, v204
	v_lshl_add_u32 v198, v206, 7, v205
	v_xor_b32_e32 v199, 64, v198
	v_add_u32_e32 v198, 0xc010, v198
	v_add_u32_e32 v199, 0xc010, v199
	v_lshrrev_b32_e32 v206, 3, v168
	v_and_b32_e32 v207, 7, v168
	v_lshrrev_b32_e32 v204, 1, v206
	v_xor_b32_e32 v207, v207, v204
	v_lshlrev_b32_e32 v207, 4, v207
	v_lshl_add_u32 v200, v206, 11, v207
	v_xor_b32_e32 v201, 64, v200
	s_lshl_b32 s42, s42, 16
	s_sub_u32 s18, s18, s42
	s_subb_u32 s19, s19, 0
	s_add_i32 s41, s54, 16
	s_add_i32 m0, s41, 0x0
	s_nop 0
	global_load_lds_dwordx4 v200, s[18:19]
	s_add_i32 m0, s41, 0x400
	s_add_u32 s52, s18, 0x4000
	s_addc_u32 s53, s19, 0
	global_load_lds_dwordx4 v201, s[52:53]
	s_add_i32 m0, s41, 0x800
	s_add_u32 s52, s18, 0x8000
	s_addc_u32 s53, s19, 0
	global_load_lds_dwordx4 v200, s[52:53]
	s_add_i32 m0, s41, 0xc00
	s_add_u32 s52, s18, 0xc000
	s_addc_u32 s53, s19, 0
	global_load_lds_dwordx4 v201, s[52:53]
	s_add_i32 m0, s54, 0xc010
	s_nop 0
	global_load_lds_dwordx4 v200, s[28:29]
	s_add_i32 m0, s54, 0xc410
	s_add_u32 s52, s28, 0x4000
	s_addc_u32 s53, s29, 0
	global_load_lds_dwordx4 v201, s[52:53]
	s_add_i32 m0, s54, 0xc810
	s_add_u32 s52, s28, 0x8000
	s_addc_u32 s53, s29, 0
	global_load_lds_dwordx4 v200, s[52:53]
	s_add_i32 m0, s54, 0xcc10
	s_add_u32 s52, s28, 0xc000
	s_addc_u32 s53, s29, 0
	global_load_lds_dwordx4 v201, s[52:53]
	s_add_u32 s50, s18, 0x20000
	s_addc_u32 s51, s19, 0
	s_add_i32 m0, s41, 0x4000
	s_nop 0
	global_load_lds_dwordx4 v200, s[50:51]
	s_add_i32 m0, s41, 0x4400
	s_add_u32 s52, s50, 0x4000
	s_addc_u32 s53, s51, 0
	global_load_lds_dwordx4 v201, s[52:53]
	s_add_i32 m0, s41, 0x4800
	s_add_u32 s52, s50, 0x8000
	s_addc_u32 s53, s51, 0
	global_load_lds_dwordx4 v200, s[52:53]
	s_add_i32 m0, s41, 0x4c00
	s_add_u32 s52, s50, 0xc000
	s_addc_u32 s53, s51, 0
	global_load_lds_dwordx4 v201, s[52:53]
	s_mov_b32 s13, 0
	s_mov_b32 s14, 0
	v_readlane_b32 s15, v242, 0
	v_readlane_b32 s41, v241, 24
	s_nop 3
	s_lshr_b32 s41, s41, 3
	s_cmp_lt_u32 s15, s41
	s_cbranch_scc0 .Lprio_done_LBB1_1180
	s_setprio 1
